# FoX band steps: causal mask per element rebased to one value with inline-constant compares, two interleaved compare/select chains (no per-element add, half the nops)
# speedup vs baseline: 1.0041x; 1.0041x over previous
.LBB0_319:
	s_add_i32 s1, s54, s79
	s_mov_b32 s8, m0
	s_mov_b32 m0, s1
	s_nop 0
	global_load_lds_dwordx4 v191, s[50:51]
	s_mov_b32 m0, s8
	s_add_i32 s55, s47, s52
	s_add_i32 s1, s55, 2
	s_cmp_lt_i32 s1, 0
	s_cbranch_scc1 .LBB0_321
	v_sub_u32_e32 v44, v187, v195
	v_add_u32_e32 v44, 0x7b, v44
	v_cmp_le_i32_e32 vcc, 32, v44
	v_cmp_le_i32_e64 s[100:101], 1, v44
	s_nop 0
	v_cndmask_b32_e32 v66, v220, v66, vcc
	v_cndmask_b32_e64 v83, v220, v83, s[100:101]
	v_cmp_le_i32_e32 vcc, 0, v44
	v_cmp_le_i32_e64 s[100:101], 33, v44
	s_nop 0
	v_cndmask_b32_e32 v82, v220, v82, vcc
	v_cndmask_b32_e64 v67, v220, v67, s[100:101]
	v_cmp_le_i32_e32 vcc, 2, v44
	v_cmp_le_i32_e64 s[100:101], 34, v44
	s_nop 0
	v_cndmask_b32_e32 v84, v220, v84, vcc
	v_cndmask_b32_e64 v68, v220, v68, s[100:101]
	v_cmp_le_i32_e32 vcc, 3, v44
	v_cmp_le_i32_e64 s[100:101], 35, v44
	s_nop 0
	v_cndmask_b32_e32 v85, v220, v85, vcc
	v_cndmask_b32_e64 v69, v220, v69, s[100:101]
	v_cmp_le_i32_e32 vcc, 8, v44
	v_cmp_le_i32_e64 s[100:101], 40, v44
	s_nop 0
	v_cndmask_b32_e32 v86, v220, v86, vcc
	v_cndmask_b32_e64 v70, v220, v70, s[100:101]
	v_cmp_le_i32_e32 vcc, 9, v44
	v_cmp_le_i32_e64 s[100:101], 41, v44
	s_nop 0
	v_cndmask_b32_e32 v87, v220, v87, vcc
	v_cndmask_b32_e64 v71, v220, v71, s[100:101]
	v_cmp_le_i32_e32 vcc, 10, v44
	v_cmp_le_i32_e64 s[100:101], 42, v44
	s_nop 0
	v_cndmask_b32_e32 v88, v220, v88, vcc
	v_cndmask_b32_e64 v72, v220, v72, s[100:101]
	v_cmp_le_i32_e32 vcc, 11, v44
	v_cmp_le_i32_e64 s[100:101], 43, v44
	s_nop 0
	v_cndmask_b32_e32 v89, v220, v89, vcc
	v_cndmask_b32_e64 v73, v220, v73, s[100:101]
	v_cmp_le_i32_e32 vcc, 16, v44
	v_cmp_le_i32_e64 s[100:101], 48, v44
	s_nop 0
	v_cndmask_b32_e32 v90, v220, v90, vcc
	v_cndmask_b32_e64 v74, v220, v74, s[100:101]
	v_cmp_le_i32_e32 vcc, 17, v44
	v_cmp_le_i32_e64 s[100:101], 49, v44
	s_nop 0
	v_cndmask_b32_e32 v91, v220, v91, vcc
	v_cndmask_b32_e64 v75, v220, v75, s[100:101]
	v_cmp_le_i32_e32 vcc, 18, v44
	v_cmp_le_i32_e64 s[100:101], 50, v44
	s_nop 0
	v_cndmask_b32_e32 v92, v220, v92, vcc
	v_cndmask_b32_e64 v76, v220, v76, s[100:101]
	v_cmp_le_i32_e32 vcc, 19, v44
	v_cmp_le_i32_e64 s[100:101], 51, v44
	s_nop 0
	v_cndmask_b32_e32 v93, v220, v93, vcc
	v_cndmask_b32_e64 v77, v220, v77, s[100:101]
	v_cmp_le_i32_e32 vcc, 24, v44
	v_cmp_le_i32_e64 s[100:101], 56, v44
	s_nop 0
	v_cndmask_b32_e32 v94, v220, v94, vcc
	v_cndmask_b32_e64 v78, v220, v78, s[100:101]
	v_cmp_le_i32_e32 vcc, 25, v44
	v_cmp_le_i32_e64 s[100:101], 57, v44
	s_nop 0
	v_cndmask_b32_e32 v95, v220, v95, vcc
	v_cndmask_b32_e64 v79, v220, v79, s[100:101]
	v_cmp_le_i32_e32 vcc, 26, v44
	v_cmp_le_i32_e64 s[100:101], 58, v44
	s_nop 0
	v_cndmask_b32_e32 v96, v220, v96, vcc
	v_cndmask_b32_e64 v80, v220, v80, s[100:101]
	v_cmp_le_i32_e32 vcc, 27, v44
	v_cmp_le_i32_e64 s[100:101], 59, v44
	s_nop 0
	v_cndmask_b32_e32 v97, v220, v97, vcc
	v_cndmask_b32_e64 v81, v220, v81, s[100:101]

.LBB0_334:
	s_add_i32 s55, s55, 3
	s_cmp_lt_i32 s55, 0
	s_cbranch_scc1 .LBB0_336
	v_sub_u32_e32 v75, v187, v195
	v_add_u32_e32 v75, 59, v75
	v_cmp_le_i32_e32 vcc, 32, v75
	v_cmp_le_i32_e64 s[100:101], 1, v75
	s_nop 0
	v_cndmask_b32_e32 v32, v220, v32, vcc
	v_cndmask_b32_e64 v49, v220, v49, s[100:101]
	v_cmp_le_i32_e32 vcc, 0, v75
	v_cmp_le_i32_e64 s[100:101], 33, v75
	s_nop 0
	v_cndmask_b32_e32 v48, v220, v48, vcc
	v_cndmask_b32_e64 v33, v220, v33, s[100:101]
	v_cmp_le_i32_e32 vcc, 2, v75
	v_cmp_le_i32_e64 s[100:101], 34, v75
	s_nop 0
	v_cndmask_b32_e32 v50, v220, v50, vcc
	v_cndmask_b32_e64 v34, v220, v34, s[100:101]
	v_cmp_le_i32_e32 vcc, 3, v75
	v_cmp_le_i32_e64 s[100:101], 35, v75
	s_nop 0
	v_cndmask_b32_e32 v51, v220, v51, vcc
	v_cndmask_b32_e64 v35, v220, v35, s[100:101]
	v_cmp_le_i32_e32 vcc, 8, v75
	v_cmp_le_i32_e64 s[100:101], 40, v75
	s_nop 0
	v_cndmask_b32_e32 v52, v220, v52, vcc
	v_cndmask_b32_e64 v36, v220, v36, s[100:101]
	v_cmp_le_i32_e32 vcc, 9, v75
	v_cmp_le_i32_e64 s[100:101], 41, v75
	s_nop 0
	v_cndmask_b32_e32 v53, v220, v53, vcc
	v_cndmask_b32_e64 v37, v220, v37, s[100:101]
	v_cmp_le_i32_e32 vcc, 10, v75
	v_cmp_le_i32_e64 s[100:101], 42, v75
	s_nop 0
	v_cndmask_b32_e32 v54, v220, v54, vcc
	v_cndmask_b32_e64 v38, v220, v38, s[100:101]
	v_cmp_le_i32_e32 vcc, 11, v75
	v_cmp_le_i32_e64 s[100:101], 43, v75
	s_nop 0
	v_cndmask_b32_e32 v55, v220, v55, vcc
	v_cndmask_b32_e64 v39, v220, v39, s[100:101]
	v_cmp_le_i32_e32 vcc, 16, v75
	v_cmp_le_i32_e64 s[100:101], 48, v75
	s_nop 0
	v_cndmask_b32_e32 v56, v220, v56, vcc
	v_cndmask_b32_e64 v40, v220, v40, s[100:101]
	v_cmp_le_i32_e32 vcc, 17, v75
	v_cmp_le_i32_e64 s[100:101], 49, v75
	s_nop 0
	v_cndmask_b32_e32 v57, v220, v57, vcc
	v_cndmask_b32_e64 v41, v220, v41, s[100:101]
	v_cmp_le_i32_e32 vcc, 18, v75
	v_cmp_le_i32_e64 s[100:101], 50, v75
	s_nop 0
	v_cndmask_b32_e32 v58, v220, v58, vcc
	v_cndmask_b32_e64 v42, v220, v42, s[100:101]
	v_cmp_le_i32_e32 vcc, 19, v75
	v_cmp_le_i32_e64 s[100:101], 51, v75
	s_nop 0
	v_cndmask_b32_e32 v59, v220, v59, vcc
	v_cndmask_b32_e64 v43, v220, v43, s[100:101]
	v_cmp_le_i32_e32 vcc, 24, v75
	v_cmp_le_i32_e64 s[100:101], 56, v75
	s_nop 0
	v_cndmask_b32_e32 v60, v220, v60, vcc
	v_cndmask_b32_e64 v44, v220, v44, s[100:101]
	v_cmp_le_i32_e32 vcc, 25, v75
	v_cmp_le_i32_e64 s[100:101], 57, v75
	s_nop 0
	v_cndmask_b32_e32 v61, v220, v61, vcc
	v_cndmask_b32_e64 v45, v220, v45, s[100:101]
	v_cmp_le_i32_e32 vcc, 26, v75
	v_cmp_le_i32_e64 s[100:101], 58, v75
	s_nop 0
	v_cndmask_b32_e32 v62, v220, v62, vcc
	v_cndmask_b32_e64 v46, v220, v46, s[100:101]
	v_cmp_le_i32_e32 vcc, 27, v75
	v_cmp_le_i32_e64 s[100:101], 59, v75
	s_nop 0
	v_cndmask_b32_e32 v63, v220, v63, vcc
	v_cndmask_b32_e64 v47, v220, v47, s[100:101]
